# sample attention first half: K fragment reads interleaved per chain with counted lgkmcnt waits so QK MFMAs start on the first fragments; shorter post-MFMA pad
# baseline (speedup 1.0000x reference)
.Lsa_no_e1:
.LBB0_377:
	s_and_b32 s22, s3, 1
	s_mul_i32 s22, s22, 0x3400
	v_add3_u32 v160, v154, s22, v155
	ds_read_b128 v[190:193], v160
	ds_read_b128 v[214:217], v160 offset:6656
	ds_read_b128 v[194:197], v160 offset:32
	ds_read_b128 v[218:221], v160 offset:6688
	ds_read_b128 v[198:201], v160 offset:64
	ds_read_b128 v[222:225], v160 offset:6720
	ds_read_b128 v[202:205], v160 offset:96
	ds_read_b128 v[226:229], v160 offset:6752
	ds_read_b128 v[206:209], v160 offset:128
	ds_read_b128 v[230:233], v160 offset:6784
	ds_read_b128 v[210:213], v160 offset:160
	ds_read_b128 v[234:237], v160 offset:6816
	s_add_i32 s2, s3, 1
	s_bitcmp1_b32 s2, 0
	s_cselect_b32 s22, 0x3400, 0
	s_cselect_b32 s23, 0x2400, 0
	s_add_i32 s22, s24, s22
	s_and_b32 s3, s3, 1
	s_cmpk_lg_i32 s1, 0x200
	s_cbranch_scc1 .Lsa_noq
	v_mov_b32_e32 v67, v95
	v_mov_b32_e32 v66, v94
	v_mov_b32_e32 v65, v93
	v_mov_b32_e32 v64, v92
	v_mov_b32_e32 v71, v91
	v_mov_b32_e32 v70, v90
	v_mov_b32_e32 v69, v89
	v_mov_b32_e32 v68, v88
.Lsa_noq:
	v_add3_u32 v160, s22, v144, v145
	v_add3_u32 v161, s22, v146, v147
	s_setprio 1
	s_waitcnt lgkmcnt(10)
	v_mfma_f32_32x32x16_bf16 v[32:47], v[190:193], v[84:87], 0
	v_mfma_f32_32x32x16_bf16 v[48:63], v[214:217], v[84:87], 0
	s_waitcnt vmcnt(4)
	ds_write_b128 v160, v[96:99]
	v_add3_u32 v160, s22, v148, v149
	s_waitcnt lgkmcnt(9)
	v_mfma_f32_32x32x16_bf16 v[32:47], v[194:197], v[80:83], v[32:47]
	v_mfma_f32_32x32x16_bf16 v[48:63], v[218:221], v[80:83], v[48:63]
	s_waitcnt vmcnt(3)
	ds_write_b128 v161, v[100:103]
	v_add_u32_e32 v161, s23, v150
	s_waitcnt lgkmcnt(8)
	v_mfma_f32_32x32x16_bf16 v[32:47], v[198:201], v[76:79], v[32:47]
	v_mfma_f32_32x32x16_bf16 v[48:63], v[222:225], v[76:79], v[48:63]
	s_waitcnt vmcnt(2)
	ds_write_b128 v160, v[104:107]
	v_add_u32_e32 v160, v161, v152
	v_add_u32_e32 v161, v161, v153
	s_waitcnt lgkmcnt(7)
	v_mfma_f32_32x32x16_bf16 v[32:47], v[202:205], v[72:75], v[32:47]
	v_mfma_f32_32x32x16_bf16 v[48:63], v[226:229], v[72:75], v[48:63]
	s_waitcnt vmcnt(1)
	ds_write_b128 v160, v[108:111] offset:26624
	s_waitcnt vmcnt(0)
	ds_write_b128 v161, v[112:115] offset:26624
	v_cndmask_b32_e64 v160, v238, v239, s[40:41]
	v_cndmask_b32_e64 v161, v238, v239, s[42:43]
	s_waitcnt lgkmcnt(7)
	v_mfma_f32_32x32x16_bf16 v[32:47], v[206:209], v[68:71], v[32:47]
	v_mfma_f32_32x32x16_bf16 v[48:63], v[230:233], v[68:71], v[48:63]
	s_cmpk_gt_u32 s2, 0x46
	s_cbranch_scc1 .Lsa_nold
	global_load_dwordx4 v[96:99], v[240:241], off
	global_load_dwordx4 v[100:103], v[242:243], off
	global_load_dwordx4 v[104:107], v[244:245], off
	global_load_dwordx4 v[108:111], v[246:247], off
	global_load_dwordx4 v[112:115], v[248:249], off
.Lsa_nold:
	v_add_co_u32_e32 v240, vcc, v240, v160
	v_addc_co_u32_e32 v241, vcc, 0, v241, vcc
	v_add_co_u32_e32 v242, vcc, v242, v161
	v_addc_co_u32_e32 v243, vcc, 0, v243, vcc
	v_cndmask_b32_e64 v160, v238, v239, s[44:45]
	s_waitcnt lgkmcnt(5)
	v_mfma_f32_32x32x16_bf16 v[32:47], v[210:213], v[64:67], v[32:47]
	v_mfma_f32_32x32x16_bf16 v[48:63], v[234:237], v[64:67], v[48:63]
	v_add_co_u32_e32 v244, vcc, v244, v160
	v_addc_co_u32_e32 v245, vcc, 0, v245, vcc
	v_add_co_u32_e32 v246, vcc, 0x80, v246
	v_addc_co_u32_e32 v247, vcc, 0, v247, vcc
	v_add_co_u32_e32 v248, vcc, 0x80, v248
	v_addc_co_u32_e32 v249, vcc, 0, v249, vcc
	s_setprio 0
	s_nop 5
	v_max_f32_e32 v121, v48, v48
	v_max_f32_e32 v159, v32, v32
	v_max_f32_e32 v121, v159, v121
	v_max3_f32 v121, v121, v33, v49
	v_max3_f32 v121, v121, v34, v50
	v_max3_f32 v121, v121, v35, v51
	v_max3_f32 v121, v121, v36, v52
	v_max3_f32 v121, v121, v37, v53
	v_max3_f32 v121, v121, v38, v54
	v_max3_f32 v121, v121, v39, v55
	v_max3_f32 v121, v121, v40, v56
	v_max3_f32 v121, v121, v41, v57
	v_max3_f32 v121, v121, v42, v58
	v_max3_f32 v121, v121, v43, v59
	v_max3_f32 v121, v121, v44, v60
	v_max3_f32 v121, v121, v45, v61
	v_max3_f32 v121, v121, v46, v62
	v_cmp_lt_i32_e32 vcc, v177, v176
	v_max3_f32 v159, v121, v47, v63
	s_nop 0
	v_cndmask_b32_e32 v121, v175, v177, vcc
	v_lshlrev_b32_e32 v121, 2, v121
	ds_bpermute_b32 v160, v121, v159
	s_waitcnt lgkmcnt(0)
	v_max_f32_e32 v160, v160, v160
	v_max_f32_e32 v159, v159, v160
	v_add_f32_e32 v160, 0x41000000, v151
	v_cmp_gt_f32_e32 vcc, v159, v160
	s_cbranch_vccz .LBB0_381
	v_max_f32_e32 v159, v159, v159
	v_max_f32_e32 v160, v151, v151
	v_max_f32_e32 v159, v160, v159
	v_sub_f32_e32 v151, v151, v159
	v_exp_f32_e32 v160, v151
	v_mov_b32_e32 v151, v159
	v_pk_mul_f32 v[30:31], v[30:31], v[160:161] op_sel_hi:[1,0]
	v_pk_mul_f32 v[28:29], v[28:29], v[160:161] op_sel_hi:[1,0]
	v_pk_mul_f32 v[26:27], v[26:27], v[160:161] op_sel_hi:[1,0]
	v_pk_mul_f32 v[24:25], v[24:25], v[160:161] op_sel_hi:[1,0]
	v_pk_mul_f32 v[22:23], v[22:23], v[160:161] op_sel_hi:[1,0]
	v_pk_mul_f32 v[20:21], v[20:21], v[160:161] op_sel_hi:[1,0]
	v_pk_mul_f32 v[18:19], v[18:19], v[160:161] op_sel_hi:[1,0]
	v_pk_mul_f32 v[16:17], v[16:17], v[160:161] op_sel_hi:[1,0]
	v_pk_mul_f32 v[14:15], v[14:15], v[160:161] op_sel_hi:[1,0]
	v_pk_mul_f32 v[12:13], v[12:13], v[160:161] op_sel_hi:[1,0]
	v_pk_mul_f32 v[10:11], v[10:11], v[160:161] op_sel_hi:[1,0]
	v_pk_mul_f32 v[8:9], v[8:9], v[160:161] op_sel_hi:[1,0]
	v_pk_mul_f32 v[6:7], v[6:7], v[160:161] op_sel_hi:[1,0]
	v_pk_mul_f32 v[4:5], v[4:5], v[160:161] op_sel_hi:[1,0]
	v_pk_mul_f32 v[2:3], v[2:3], v[160:161] op_sel_hi:[1,0]
	v_pk_mul_f32 v[0:1], v[0:1], v[160:161] op_sel_hi:[1,0]
	v_mul_f32_e32 v119, v119, v160
